# in-proj GEMM epilogue: 4 rotary-table loads issued together (one wait instead of two), each row-group's stores deferred behind the next row-group's loads
# speedup vs baseline: 1.0063x; 1.0061x over previous
; DI unsigned pk2(float lo, float hi) { typedef float f2 __attribute__((ext_vector_type(2))); typedef __bf16 b2 __attribute__((ext_vector_type(2))); f2 v = {lo, hi}; b2 b = __builtin_convertvector(v, b2); return __builtin_bit_cast(unsigned, b); }
;     DI void operator()(const f32x4 (&acc)[2][2][4][2], const Unit& u, int wr, int wc, int fr, int fq) const {
;     ...
;                     if (fq == 0) { const float* t = trigD + (size_t)pos * 16;
; #pragma unroll
;                         for (int n = 0; n < 2; ++n) { const f32x4 c4 = *(const f32x4*)(t + 4 * n), s4 = *(const f32x4*)(t + 8 + 4 * n); const f32x4 x1 = v[0][n], x2 = v[1][n];
;                             v[0][n] = x1 * c4 - x2 * s4; v[1][n] = x1 * s4 + x2 * c4; } }
;                 } else if (isrot) { const float* t = trigR + (size_t)pos * 64 + 8 * fq;
; #pragma unroll
;                     for (int n = 0; n < 2; ++n) { const f32x4 c4 = *(const f32x4*)(t + 4 * n), s4 = *(const f32x4*)(t + 32 + 4 * n); const f32x4 x1 = v[0][n], x2 = v[1][n];
;                         v[0][n] = x1 * c4 - x2 * s4; v[1][n] = x1 * s4 + x2 * c4; }
;                 }
;                 bf16_t* rowp = base + (size_t)row * ld + col0;
; #pragma unroll
;                 for (int bj = 0; bj < 2; ++bj) { const f32x4 v0 = v[bj][0] * osc, v1 = v[bj][1] * osc;
;                     u32x4 o; o.x = pk2(v0[0], v0[1]); o.y = pk2(v0[2], v0[3]); o.z = pk2(v1[0], v1[1]); o.w = pk2(v1[2], v1[3]);
;                     *(u32x4*)(rowp + 32 * bj) = o; }
.LBB0_478:
	v_and_b32_e32 v192, s4, v158
	v_lshlrev_b64 v[114:115], s50, v[192:193]
	v_lshl_add_u64 v[204:205], v[112:113], 0, v[114:115]
	v_lshl_add_u64 v[196:197], v[204:205], 0, s[56:57]
	v_lshl_add_u64 v[212:213], v[204:205], 0, vcc
	global_load_dwordx4 v[112:115], v[204:205], off offset:16
	global_load_dwordx4 v[188:191], v[204:205], off
	s_nop 0
	global_load_dwordx4 v[196:199], v[196:197], off
	global_load_dwordx4 v[208:211], v[212:213], off
	s_waitcnt vmcnt(0)
	v_pk_mul_f32 v[200:201], v[118:119], v[198:199]
	v_pk_mul_f32 v[206:207], v[116:117], v[196:197]
	v_pk_fma_f32 v[202:203], v[126:127], v[190:191], v[200:201] neg_lo:[0,0,1] neg_hi:[0,0,1]
	v_pk_fma_f32 v[200:201], v[124:125], v[188:189], v[206:207] neg_lo:[0,0,1] neg_hi:[0,0,1]
	v_pk_mul_f32 v[124:125], v[124:125], v[196:197]
	v_pk_mul_f32 v[126:127], v[126:127], v[198:199]
	v_pk_fma_f32 v[116:117], v[116:117], v[188:189], v[124:125]
	v_pk_fma_f32 v[118:119], v[118:119], v[190:191], v[126:127]
	v_pk_mul_f32 v[188:189], v[160:161], v[210:211]
	v_pk_mul_f32 v[196:197], v[162:163], v[208:209]
	v_pk_fma_f32 v[190:191], v[122:123], v[114:115], v[188:189] neg_lo:[0,0,1] neg_hi:[0,0,1]
	v_pk_fma_f32 v[188:189], v[120:121], v[112:113], v[196:197] neg_lo:[0,0,1] neg_hi:[0,0,1]
	v_pk_mul_f32 v[122:123], v[122:123], v[210:211]
	v_pk_mul_f32 v[120:121], v[120:121], v[208:209]
	v_pk_fma_f32 v[160:161], v[160:161], v[114:115], v[122:123]
	v_pk_fma_f32 v[162:163], v[162:163], v[112:113], v[120:121]
	v_mov_b64_e32 v[120:121], v[188:189]
	v_mov_b64_e32 v[124:125], v[200:201]
	v_mov_b64_e32 v[122:123], v[190:191]
	v_mov_b64_e32 v[126:127], v[202:203]
.LBB0_479:
	s_or_b64 exec, exec, s[88:89]
	s_lshl_b32 s8, s30, 8
	s_add_i32 s9, s8, 0xfffffc00
	s_cmp_eq_u32 s53, 4
	s_cselect_b64 vcc, -1, 0
	s_cmp_lt_i32 s30, 4
	v_mov_b32_e32 v112, 0x3e000000
	s_cselect_b32 s8, s8, s9
	v_cndmask_b32_e32 v112, 1.0, v112, vcc
	s_cselect_b32 s9, s29, s49
	s_cselect_b32 s10, s28, s48
	v_or_b32_e32 v188, s8, v169
	v_mov_b32_e32 v113, 0x3e38aa3b
	s_movk_i32 s8, 0xa00
	v_mov_b32_e32 v114, s10
	v_mov_b32_e32 v115, s9
	v_cndmask_b32_e64 v112, v112, v113, s[42:43]
	v_ashrrev_i32_e32 v189, 31, v188
	s_cselect_b32 s61, 0x400, s8
	v_lshl_add_u64 v[114:115], v[188:189], 1, v[114:115]
	v_mad_i64_i32 v[188:189], s[8:9], s61, v158, 0
	v_pk_mul_f32 v[126:127], v[112:113], v[126:127] op_sel_hi:[0,1]
	v_pk_mul_f32 v[124:125], v[112:113], v[124:125] op_sel_hi:[0,1]
	v_pk_mul_f32 v[190:191], v[112:113], v[122:123] op_sel_hi:[0,1]
	v_pk_mul_f32 v[122:123], v[112:113], v[120:121] op_sel_hi:[0,1]
	v_lshl_add_u64 v[214:215], v[188:189], 1, v[114:115]
	v_cvt_pk_bf16_f32 v216, v124, v125
	v_cvt_pk_bf16_f32 v217, v126, v127
	v_cvt_pk_bf16_f32 v218, v122, v123
	v_cvt_pk_bf16_f32 v219, v190, v191
	v_pk_mul_f32 v[118:119], v[112:113], v[118:119] op_sel_hi:[0,1]
	v_pk_mul_f32 v[116:117], v[112:113], v[116:117] op_sel_hi:[0,1]
	v_pk_mul_f32 v[120:121], v[112:113], v[160:161] op_sel_hi:[0,1]
	v_pk_mul_f32 v[122:123], v[112:113], v[162:163] op_sel_hi:[0,1]
	v_cvt_pk_bf16_f32 v220, v116, v117
	v_cvt_pk_bf16_f32 v221, v118, v119
	v_cvt_pk_bf16_f32 v222, v122, v123
	v_cvt_pk_bf16_f32 v223, v120, v121
	v_cndmask_b32_e64 v113, 0, 1, s[44:45]
	v_cmp_ne_u32_e64 s[42:43], 1, v113
	s_andn2_b64 vcc, exec, s[44:45]
	v_or_b32_e32 v116, 16, v158
	s_mov_b64 s[30:31], -1
	s_cbranch_vccz .LBB0_484
	s_andn2_b64 vcc, exec, s[30:31]
	s_cbranch_vccz .LBB0_485

; DI unsigned pk2(float lo, float hi) { typedef float f2 __attribute__((ext_vector_type(2))); typedef __bf16 b2 __attribute__((ext_vector_type(2))); f2 v = {lo, hi}; b2 b = __builtin_convertvector(v, b2); return __builtin_bit_cast(unsigned, b); }
;     DI void operator()(const f32x4 (&acc)[2][2][4][2], const Unit& u, int wr, int wc, int fr, int fq) const {
;     ...
;                     if (fq == 0) { const float* t = trigD + (size_t)pos * 16;
; #pragma unroll
;                         for (int n = 0; n < 2; ++n) { const f32x4 c4 = *(const f32x4*)(t + 4 * n), s4 = *(const f32x4*)(t + 8 + 4 * n); const f32x4 x1 = v[0][n], x2 = v[1][n];
;                             v[0][n] = x1 * c4 - x2 * s4; v[1][n] = x1 * s4 + x2 * c4; } }
;                 } else if (isrot) { const float* t = trigR + (size_t)pos * 64 + 8 * fq;
; #pragma unroll
;                     for (int n = 0; n < 2; ++n) { const f32x4 c4 = *(const f32x4*)(t + 4 * n), s4 = *(const f32x4*)(t + 32 + 4 * n); const f32x4 x1 = v[0][n], x2 = v[1][n];
;                         v[0][n] = x1 * c4 - x2 * s4; v[1][n] = x1 * s4 + x2 * c4; }
;                 }
;                 bf16_t* rowp = base + (size_t)row * ld + col0;
; #pragma unroll
;                 for (int bj = 0; bj < 2; ++bj) { const f32x4 v0 = v[bj][0] * osc, v1 = v[bj][1] * osc;
;                     u32x4 o; o.x = pk2(v0[0], v0[1]); o.y = pk2(v0[2], v0[3]); o.z = pk2(v1[0], v1[1]); o.w = pk2(v1[2], v1[3]);
;                     *(u32x4*)(rowp + 32 * bj) = o; }
.LBB0_493:
	v_and_b32_e32 v192, s4, v116
	v_lshlrev_b64 v[120:121], s56, v[192:193]
	v_lshl_add_u64 v[126:127], v[118:119], 0, v[120:121]
	v_lshl_add_u64 v[160:161], v[126:127], 0, s[50:51]
	v_lshl_add_u64 v[212:213], v[126:127], 0, s[86:87]
	global_load_dwordx4 v[118:121], v[126:127], off offset:16
	global_load_dwordx4 v[122:125], v[126:127], off
	s_nop 0
	global_load_dwordx4 v[160:163], v[160:161], off
	global_load_dwordx4 v[208:211], v[212:213], off
	s_waitcnt vmcnt(0)
	v_pk_mul_f32 v[188:189], v[102:103], v[162:163]
	v_pk_mul_f32 v[196:197], v[100:101], v[160:161]
	v_pk_fma_f32 v[190:191], v[110:111], v[124:125], v[188:189] neg_lo:[0,0,1] neg_hi:[0,0,1]
	v_pk_fma_f32 v[188:189], v[108:109], v[122:123], v[196:197] neg_lo:[0,0,1] neg_hi:[0,0,1]
	v_pk_mul_f32 v[108:109], v[108:109], v[160:161]
	v_pk_mul_f32 v[110:111], v[110:111], v[162:163]
	v_pk_fma_f32 v[100:101], v[100:101], v[122:123], v[108:109]
	v_pk_fma_f32 v[102:103], v[102:103], v[124:125], v[110:111]
	v_pk_mul_f32 v[122:123], v[98:99], v[210:211]
	v_pk_mul_f32 v[126:127], v[96:97], v[208:209]
	v_pk_fma_f32 v[124:125], v[106:107], v[120:121], v[122:123] neg_lo:[0,0,1] neg_hi:[0,0,1]
	v_pk_fma_f32 v[122:123], v[104:105], v[118:119], v[126:127] neg_lo:[0,0,1] neg_hi:[0,0,1]
	v_pk_mul_f32 v[106:107], v[106:107], v[210:211]
	v_pk_mul_f32 v[104:105], v[104:105], v[208:209]
	v_pk_fma_f32 v[98:99], v[98:99], v[120:121], v[106:107]
	v_pk_fma_f32 v[96:97], v[96:97], v[118:119], v[104:105]
	v_mov_b64_e32 v[104:105], v[122:123]
	v_mov_b64_e32 v[108:109], v[188:189]
	v_mov_b64_e32 v[106:107], v[124:125]
	v_mov_b64_e32 v[110:111], v[190:191]
.LBB0_494:
	s_or_b64 exec, exec, s[30:31]
	global_store_dwordx4 v[214:215], v[216:219], off
	global_store_dwordx4 v[214:215], v[220:223], off offset:64
	v_mov_b32_e32 v113, v112
	v_mov_b32_e32 v118, v112
	v_mov_b32_e32 v119, v112
	v_mad_i64_i32 v[116:117], s[0:1], s61, v116, 0
	v_pk_mul_f32 v[110:111], v[118:119], v[110:111]
	v_pk_mul_f32 v[108:109], v[112:113], v[108:109]
	v_pk_mul_f32 v[120:121], v[118:119], v[106:107]
	v_pk_mul_f32 v[106:107], v[112:113], v[104:105]
	v_lshl_add_u64 v[224:225], v[116:117], 1, v[114:115]
	v_cvt_pk_bf16_f32 v226, v108, v109
	v_cvt_pk_bf16_f32 v227, v110, v111
	v_cvt_pk_bf16_f32 v228, v106, v107
	v_cvt_pk_bf16_f32 v229, v120, v121
	v_pk_mul_f32 v[102:103], v[118:119], v[102:103]
	v_pk_mul_f32 v[100:101], v[112:113], v[100:101]
	v_pk_mul_f32 v[104:105], v[118:119], v[98:99]
	v_pk_mul_f32 v[98:99], v[112:113], v[96:97]
	v_cvt_pk_bf16_f32 v230, v100, v101
	v_cvt_pk_bf16_f32 v231, v102, v103
	v_cvt_pk_bf16_f32 v232, v98, v99
	v_cvt_pk_bf16_f32 v233, v104, v105
	s_and_b64 vcc, exec, s[42:43]
	s_mov_b64 s[0:1], -1
	v_or_b32_e32 v96, 32, v158
	s_cbranch_vccz .LBB0_499
	s_andn2_b64 vcc, exec, s[0:1]
	s_cbranch_vccz .LBB0_500

; DI unsigned pk2(float lo, float hi) { typedef float f2 __attribute__((ext_vector_type(2))); typedef __bf16 b2 __attribute__((ext_vector_type(2))); f2 v = {lo, hi}; b2 b = __builtin_convertvector(v, b2); return __builtin_bit_cast(unsigned, b); }
;     DI void operator()(const f32x4 (&acc)[2][2][4][2], const Unit& u, int wr, int wc, int fr, int fq) const {
;     ...
;                     if (fq == 0) { const float* t = trigD + (size_t)pos * 16;
; #pragma unroll
;                         for (int n = 0; n < 2; ++n) { const f32x4 c4 = *(const f32x4*)(t + 4 * n), s4 = *(const f32x4*)(t + 8 + 4 * n); const f32x4 x1 = v[0][n], x2 = v[1][n];
;                             v[0][n] = x1 * c4 - x2 * s4; v[1][n] = x1 * s4 + x2 * c4; } }
;                 } else if (isrot) { const float* t = trigR + (size_t)pos * 64 + 8 * fq;
; #pragma unroll
;                     for (int n = 0; n < 2; ++n) { const f32x4 c4 = *(const f32x4*)(t + 4 * n), s4 = *(const f32x4*)(t + 32 + 4 * n); const f32x4 x1 = v[0][n], x2 = v[1][n];
;                         v[0][n] = x1 * c4 - x2 * s4; v[1][n] = x1 * s4 + x2 * c4; }
;                 }
;                 bf16_t* rowp = base + (size_t)row * ld + col0;
; #pragma unroll
;                 for (int bj = 0; bj < 2; ++bj) { const f32x4 v0 = v[bj][0] * osc, v1 = v[bj][1] * osc;
;                     u32x4 o; o.x = pk2(v0[0], v0[1]); o.y = pk2(v0[2], v0[3]); o.z = pk2(v1[0], v1[1]); o.w = pk2(v1[2], v1[3]);
;                     *(u32x4*)(rowp + 32 * bj) = o; }
.LBB0_508:
	v_and_b32_e32 v192, s4, v96
	v_lshlrev_b64 v[100:101], s56, v[192:193]
	v_lshl_add_u64 v[110:111], v[98:99], 0, v[100:101]
	v_lshl_add_u64 v[106:107], v[110:111], 0, s[50:51]
	v_lshl_add_u64 v[212:213], v[110:111], 0, s[86:87]
	global_load_dwordx4 v[98:101], v[110:111], off offset:16
	global_load_dwordx4 v[102:105], v[110:111], off
	s_nop 0
	global_load_dwordx4 v[106:109], v[106:107], off
	global_load_dwordx4 v[208:211], v[212:213], off
	s_waitcnt vmcnt(0)
	v_pk_mul_f32 v[116:117], v[86:87], v[108:109]
	v_pk_mul_f32 v[120:121], v[84:85], v[106:107]
	v_pk_fma_f32 v[118:119], v[94:95], v[104:105], v[116:117] neg_lo:[0,0,1] neg_hi:[0,0,1]
	v_pk_fma_f32 v[116:117], v[92:93], v[102:103], v[120:121] neg_lo:[0,0,1] neg_hi:[0,0,1]
	v_pk_mul_f32 v[92:93], v[92:93], v[106:107]
	v_pk_mul_f32 v[94:95], v[94:95], v[108:109]
	v_pk_fma_f32 v[84:85], v[84:85], v[102:103], v[92:93]
	v_pk_fma_f32 v[86:87], v[86:87], v[104:105], v[94:95]
	v_pk_mul_f32 v[102:103], v[82:83], v[210:211]
	v_pk_mul_f32 v[106:107], v[80:81], v[208:209]
	v_pk_fma_f32 v[104:105], v[90:91], v[100:101], v[102:103] neg_lo:[0,0,1] neg_hi:[0,0,1]
	v_pk_fma_f32 v[102:103], v[88:89], v[98:99], v[106:107] neg_lo:[0,0,1] neg_hi:[0,0,1]
	v_pk_mul_f32 v[90:91], v[90:91], v[210:211]
	v_pk_mul_f32 v[88:89], v[88:89], v[208:209]
	v_pk_fma_f32 v[82:83], v[82:83], v[100:101], v[90:91]
	v_pk_fma_f32 v[80:81], v[80:81], v[98:99], v[88:89]
	v_mov_b64_e32 v[88:89], v[102:103]
	v_mov_b64_e32 v[92:93], v[116:117]
	v_mov_b64_e32 v[90:91], v[104:105]
	v_mov_b64_e32 v[94:95], v[118:119]
.LBB0_509:
	s_or_b64 exec, exec, s[30:31]
	global_store_dwordx4 v[224:225], v[226:229], off
	global_store_dwordx4 v[224:225], v[230:233], off offset:64
	v_mov_b32_e32 v98, v112
	v_mov_b32_e32 v99, v112
	v_mad_i64_i32 v[96:97], s[0:1], s61, v96, 0
	v_pk_mul_f32 v[94:95], v[98:99], v[94:95]
	v_pk_mul_f32 v[92:93], v[112:113], v[92:93]
	v_pk_mul_f32 v[100:101], v[98:99], v[90:91]
	v_pk_mul_f32 v[90:91], v[112:113], v[88:89]
	v_lshl_add_u64 v[214:215], v[96:97], 1, v[114:115]
	v_cvt_pk_bf16_f32 v216, v92, v93
	v_cvt_pk_bf16_f32 v217, v94, v95
	v_cvt_pk_bf16_f32 v218, v90, v91
	v_cvt_pk_bf16_f32 v219, v100, v101
	v_pk_mul_f32 v[86:87], v[98:99], v[86:87]
	v_pk_mul_f32 v[84:85], v[112:113], v[84:85]
	v_pk_mul_f32 v[88:89], v[98:99], v[82:83]
	v_pk_mul_f32 v[82:83], v[112:113], v[80:81]
	v_cvt_pk_bf16_f32 v220, v84, v85
	v_cvt_pk_bf16_f32 v221, v86, v87
	v_cvt_pk_bf16_f32 v222, v82, v83
	v_cvt_pk_bf16_f32 v223, v88, v89
	s_and_b64 vcc, exec, s[42:43]
	s_mov_b64 s[0:1], -1
	v_or_b32_e32 v80, 48, v158
	s_cbranch_vccz .LBB0_514
	s_andn2_b64 vcc, exec, s[0:1]
	s_cbranch_vccz .LBB0_515

; DI unsigned pk2(float lo, float hi) { typedef float f2 __attribute__((ext_vector_type(2))); typedef __bf16 b2 __attribute__((ext_vector_type(2))); f2 v = {lo, hi}; b2 b = __builtin_convertvector(v, b2); return __builtin_bit_cast(unsigned, b); }
;     DI void operator()(const f32x4 (&acc)[2][2][4][2], const Unit& u, int wr, int wc, int fr, int fq) const {
;     ...
;                     if (fq == 0) { const float* t = trigD + (size_t)pos * 16;
; #pragma unroll
;                         for (int n = 0; n < 2; ++n) { const f32x4 c4 = *(const f32x4*)(t + 4 * n), s4 = *(const f32x4*)(t + 8 + 4 * n); const f32x4 x1 = v[0][n], x2 = v[1][n];
;                             v[0][n] = x1 * c4 - x2 * s4; v[1][n] = x1 * s4 + x2 * c4; } }
;                 } else if (isrot) { const float* t = trigR + (size_t)pos * 64 + 8 * fq;
; #pragma unroll
;                     for (int n = 0; n < 2; ++n) { const f32x4 c4 = *(const f32x4*)(t + 4 * n), s4 = *(const f32x4*)(t + 32 + 4 * n); const f32x4 x1 = v[0][n], x2 = v[1][n];
;                         v[0][n] = x1 * c4 - x2 * s4; v[1][n] = x1 * s4 + x2 * c4; }
;                 }
;                 bf16_t* rowp = base + (size_t)row * ld + col0;
; #pragma unroll
;                 for (int bj = 0; bj < 2; ++bj) { const f32x4 v0 = v[bj][0] * osc, v1 = v[bj][1] * osc;
;                     u32x4 o; o.x = pk2(v0[0], v0[1]); o.y = pk2(v0[2], v0[3]); o.z = pk2(v1[0], v1[1]); o.w = pk2(v1[2], v1[3]);
;                     *(u32x4*)(rowp + 32 * bj) = o; }
.LBB0_523:
	v_and_b32_e32 v192, s4, v80
	v_lshlrev_b64 v[84:85], s56, v[192:193]
	v_lshl_add_u64 v[98:99], v[82:83], 0, v[84:85]
	v_lshl_add_u64 v[90:91], v[98:99], 0, s[50:51]
	v_lshl_add_u64 v[212:213], v[98:99], 0, s[86:87]
	global_load_dwordx4 v[82:85], v[98:99], off offset:16
	global_load_dwordx4 v[86:89], v[98:99], off
	s_nop 0
	global_load_dwordx4 v[90:93], v[90:91], off
	global_load_dwordx4 v[208:211], v[212:213], off
	s_waitcnt vmcnt(0)
	v_pk_mul_f32 v[94:95], v[70:71], v[92:93]
	v_pk_mul_f32 v[100:101], v[68:69], v[90:91]
	v_pk_fma_f32 v[96:97], v[78:79], v[88:89], v[94:95] neg_lo:[0,0,1] neg_hi:[0,0,1]
	v_pk_fma_f32 v[94:95], v[76:77], v[86:87], v[100:101] neg_lo:[0,0,1] neg_hi:[0,0,1]
	v_pk_mul_f32 v[76:77], v[76:77], v[90:91]
	v_pk_mul_f32 v[78:79], v[78:79], v[92:93]
	v_pk_fma_f32 v[68:69], v[68:69], v[86:87], v[76:77]
	v_pk_fma_f32 v[70:71], v[70:71], v[88:89], v[78:79]
	v_pk_mul_f32 v[86:87], v[66:67], v[210:211]
	v_pk_mul_f32 v[90:91], v[64:65], v[208:209]
	v_pk_fma_f32 v[88:89], v[74:75], v[84:85], v[86:87] neg_lo:[0,0,1] neg_hi:[0,0,1]
	v_pk_fma_f32 v[86:87], v[72:73], v[82:83], v[90:91] neg_lo:[0,0,1] neg_hi:[0,0,1]
	v_pk_mul_f32 v[74:75], v[74:75], v[210:211]
	v_pk_mul_f32 v[72:73], v[72:73], v[208:209]
	v_pk_fma_f32 v[66:67], v[66:67], v[84:85], v[74:75]
	v_pk_fma_f32 v[64:65], v[64:65], v[82:83], v[72:73]
	v_mov_b64_e32 v[72:73], v[86:87]
	v_mov_b64_e32 v[76:77], v[94:95]
	v_mov_b64_e32 v[74:75], v[88:89]
	v_mov_b64_e32 v[78:79], v[96:97]
.LBB0_524:
	s_or_b64 exec, exec, s[30:31]
	global_store_dwordx4 v[214:215], v[216:219], off
	global_store_dwordx4 v[214:215], v[220:223], off offset:64
	v_mov_b32_e32 v82, v112
	v_mov_b32_e32 v83, v112
	v_mad_i64_i32 v[80:81], s[0:1], s61, v80, 0
	v_pk_mul_f32 v[78:79], v[82:83], v[78:79]
	v_pk_mul_f32 v[76:77], v[112:113], v[76:77]
	v_pk_mul_f32 v[84:85], v[82:83], v[74:75]
	v_pk_mul_f32 v[74:75], v[112:113], v[72:73]
	v_lshl_add_u64 v[224:225], v[80:81], 1, v[114:115]
	v_cvt_pk_bf16_f32 v226, v76, v77
	v_cvt_pk_bf16_f32 v227, v78, v79
	v_cvt_pk_bf16_f32 v228, v74, v75
	v_cvt_pk_bf16_f32 v229, v84, v85
	v_pk_mul_f32 v[70:71], v[82:83], v[70:71]
	v_pk_mul_f32 v[68:69], v[112:113], v[68:69]
	v_pk_mul_f32 v[72:73], v[82:83], v[66:67]
	v_pk_mul_f32 v[66:67], v[112:113], v[64:65]
	v_cvt_pk_bf16_f32 v230, v68, v69
	v_cvt_pk_bf16_f32 v231, v70, v71
	v_cvt_pk_bf16_f32 v232, v66, v67
	v_cvt_pk_bf16_f32 v233, v72, v73
	s_and_b64 vcc, exec, s[42:43]
	s_mov_b64 s[0:1], -1
	v_add_u32_e32 v64, 0x80, v158
	s_cbranch_vccz .LBB0_529
	s_andn2_b64 vcc, exec, s[0:1]
	s_cbranch_vccz .LBB0_530

; DI unsigned pk2(float lo, float hi) { typedef float f2 __attribute__((ext_vector_type(2))); typedef __bf16 b2 __attribute__((ext_vector_type(2))); f2 v = {lo, hi}; b2 b = __builtin_convertvector(v, b2); return __builtin_bit_cast(unsigned, b); }
;     DI void operator()(const f32x4 (&acc)[2][2][4][2], const Unit& u, int wr, int wc, int fr, int fq) const {
;     ...
;                     if (fq == 0) { const float* t = trigD + (size_t)pos * 16;
; #pragma unroll
;                         for (int n = 0; n < 2; ++n) { const f32x4 c4 = *(const f32x4*)(t + 4 * n), s4 = *(const f32x4*)(t + 8 + 4 * n); const f32x4 x1 = v[0][n], x2 = v[1][n];
;                             v[0][n] = x1 * c4 - x2 * s4; v[1][n] = x1 * s4 + x2 * c4; } }
;                 } else if (isrot) { const float* t = trigR + (size_t)pos * 64 + 8 * fq;
; #pragma unroll
;                     for (int n = 0; n < 2; ++n) { const f32x4 c4 = *(const f32x4*)(t + 4 * n), s4 = *(const f32x4*)(t + 32 + 4 * n); const f32x4 x1 = v[0][n], x2 = v[1][n];
;                         v[0][n] = x1 * c4 - x2 * s4; v[1][n] = x1 * s4 + x2 * c4; }
;                 }
;                 bf16_t* rowp = base + (size_t)row * ld + col0;
; #pragma unroll
;                 for (int bj = 0; bj < 2; ++bj) { const f32x4 v0 = v[bj][0] * osc, v1 = v[bj][1] * osc;
;                     u32x4 o; o.x = pk2(v0[0], v0[1]); o.y = pk2(v0[2], v0[3]); o.z = pk2(v1[0], v1[1]); o.w = pk2(v1[2], v1[3]);
;                     *(u32x4*)(rowp + 32 * bj) = o; }
.LBB0_538:
	v_and_b32_e32 v192, s4, v64
	v_lshlrev_b64 v[68:69], s56, v[192:193]
	v_lshl_add_u64 v[82:83], v[66:67], 0, v[68:69]
	v_lshl_add_u64 v[74:75], v[82:83], 0, s[50:51]
	v_lshl_add_u64 v[212:213], v[82:83], 0, s[86:87]
	global_load_dwordx4 v[66:69], v[82:83], off offset:16
	global_load_dwordx4 v[70:73], v[82:83], off
	s_nop 0
	global_load_dwordx4 v[74:77], v[74:75], off
	global_load_dwordx4 v[208:211], v[212:213], off
	s_waitcnt vmcnt(0)
	v_pk_mul_f32 v[78:79], v[54:55], v[76:77]
	v_pk_mul_f32 v[84:85], v[52:53], v[74:75]
	v_pk_fma_f32 v[80:81], v[62:63], v[72:73], v[78:79] neg_lo:[0,0,1] neg_hi:[0,0,1]
	v_pk_fma_f32 v[78:79], v[60:61], v[70:71], v[84:85] neg_lo:[0,0,1] neg_hi:[0,0,1]
	v_pk_mul_f32 v[60:61], v[60:61], v[74:75]
	v_pk_mul_f32 v[62:63], v[62:63], v[76:77]
	v_pk_fma_f32 v[52:53], v[52:53], v[70:71], v[60:61]
	v_pk_fma_f32 v[54:55], v[54:55], v[72:73], v[62:63]
	v_pk_mul_f32 v[70:71], v[50:51], v[210:211]
	v_pk_mul_f32 v[74:75], v[48:49], v[208:209]
	v_pk_fma_f32 v[72:73], v[58:59], v[68:69], v[70:71] neg_lo:[0,0,1] neg_hi:[0,0,1]
	v_pk_fma_f32 v[70:71], v[56:57], v[66:67], v[74:75] neg_lo:[0,0,1] neg_hi:[0,0,1]
	v_pk_mul_f32 v[58:59], v[58:59], v[210:211]
	v_pk_mul_f32 v[56:57], v[56:57], v[208:209]
	v_pk_fma_f32 v[50:51], v[50:51], v[68:69], v[58:59]
	v_pk_fma_f32 v[48:49], v[48:49], v[66:67], v[56:57]
	v_mov_b64_e32 v[56:57], v[70:71]
	v_mov_b64_e32 v[60:61], v[78:79]
	v_mov_b64_e32 v[58:59], v[72:73]
	v_mov_b64_e32 v[62:63], v[80:81]
.LBB0_539:
	s_or_b64 exec, exec, s[30:31]
	global_store_dwordx4 v[224:225], v[226:229], off
	global_store_dwordx4 v[224:225], v[230:233], off offset:64
	v_mov_b32_e32 v66, v112
	v_mov_b32_e32 v67, v112
	v_mad_i64_i32 v[64:65], s[0:1], s61, v64, 0
	v_pk_mul_f32 v[62:63], v[66:67], v[62:63]
	v_pk_mul_f32 v[60:61], v[112:113], v[60:61]
	v_pk_mul_f32 v[68:69], v[66:67], v[58:59]
	v_pk_mul_f32 v[58:59], v[112:113], v[56:57]
	v_lshl_add_u64 v[214:215], v[64:65], 1, v[114:115]
	v_cvt_pk_bf16_f32 v216, v60, v61
	v_cvt_pk_bf16_f32 v217, v62, v63
	v_cvt_pk_bf16_f32 v218, v58, v59
	v_cvt_pk_bf16_f32 v219, v68, v69
	v_pk_mul_f32 v[54:55], v[66:67], v[54:55]
	v_pk_mul_f32 v[52:53], v[112:113], v[52:53]
	v_pk_mul_f32 v[56:57], v[66:67], v[50:51]
	v_pk_mul_f32 v[50:51], v[112:113], v[48:49]
	v_cvt_pk_bf16_f32 v220, v52, v53
	v_cvt_pk_bf16_f32 v221, v54, v55
	v_cvt_pk_bf16_f32 v222, v50, v51
	v_cvt_pk_bf16_f32 v223, v56, v57
	s_and_b64 vcc, exec, s[42:43]
	s_mov_b64 s[0:1], -1
	v_add_u32_e32 v48, 0x90, v158
	s_cbranch_vccz .LBB0_544
	s_andn2_b64 vcc, exec, s[0:1]
	s_cbranch_vccz .LBB0_545

; DI unsigned pk2(float lo, float hi) { typedef float f2 __attribute__((ext_vector_type(2))); typedef __bf16 b2 __attribute__((ext_vector_type(2))); f2 v = {lo, hi}; b2 b = __builtin_convertvector(v, b2); return __builtin_bit_cast(unsigned, b); }
;     DI void operator()(const f32x4 (&acc)[2][2][4][2], const Unit& u, int wr, int wc, int fr, int fq) const {
;     ...
;                     if (fq == 0) { const float* t = trigD + (size_t)pos * 16;
; #pragma unroll
;                         for (int n = 0; n < 2; ++n) { const f32x4 c4 = *(const f32x4*)(t + 4 * n), s4 = *(const f32x4*)(t + 8 + 4 * n); const f32x4 x1 = v[0][n], x2 = v[1][n];
;                             v[0][n] = x1 * c4 - x2 * s4; v[1][n] = x1 * s4 + x2 * c4; } }
;                 } else if (isrot) { const float* t = trigR + (size_t)pos * 64 + 8 * fq;
; #pragma unroll
;                     for (int n = 0; n < 2; ++n) { const f32x4 c4 = *(const f32x4*)(t + 4 * n), s4 = *(const f32x4*)(t + 32 + 4 * n); const f32x4 x1 = v[0][n], x2 = v[1][n];
;                         v[0][n] = x1 * c4 - x2 * s4; v[1][n] = x1 * s4 + x2 * c4; }
;                 }
;                 bf16_t* rowp = base + (size_t)row * ld + col0;
; #pragma unroll
;                 for (int bj = 0; bj < 2; ++bj) { const f32x4 v0 = v[bj][0] * osc, v1 = v[bj][1] * osc;
;                     u32x4 o; o.x = pk2(v0[0], v0[1]); o.y = pk2(v0[2], v0[3]); o.z = pk2(v1[0], v1[1]); o.w = pk2(v1[2], v1[3]);
;                     *(u32x4*)(rowp + 32 * bj) = o; }
.LBB0_553:
	v_and_b32_e32 v192, s4, v48
	v_lshlrev_b64 v[52:53], s56, v[192:193]
	v_lshl_add_u64 v[66:67], v[50:51], 0, v[52:53]
	v_lshl_add_u64 v[58:59], v[66:67], 0, s[50:51]
	v_lshl_add_u64 v[212:213], v[66:67], 0, s[86:87]
	global_load_dwordx4 v[50:53], v[66:67], off offset:16
	global_load_dwordx4 v[54:57], v[66:67], off
	s_nop 0
	global_load_dwordx4 v[58:61], v[58:59], off
	global_load_dwordx4 v[208:211], v[212:213], off
	s_waitcnt vmcnt(0)
	v_pk_mul_f32 v[62:63], v[38:39], v[60:61]
	v_pk_mul_f32 v[68:69], v[36:37], v[58:59]
	v_pk_fma_f32 v[64:65], v[46:47], v[56:57], v[62:63] neg_lo:[0,0,1] neg_hi:[0,0,1]
	v_pk_fma_f32 v[62:63], v[44:45], v[54:55], v[68:69] neg_lo:[0,0,1] neg_hi:[0,0,1]
	v_pk_mul_f32 v[44:45], v[44:45], v[58:59]
	v_pk_mul_f32 v[46:47], v[46:47], v[60:61]
	v_pk_fma_f32 v[36:37], v[36:37], v[54:55], v[44:45]
	v_pk_fma_f32 v[38:39], v[38:39], v[56:57], v[46:47]
	v_pk_mul_f32 v[54:55], v[34:35], v[210:211]
	v_pk_mul_f32 v[58:59], v[32:33], v[208:209]
	v_pk_fma_f32 v[56:57], v[42:43], v[52:53], v[54:55] neg_lo:[0,0,1] neg_hi:[0,0,1]
	v_pk_fma_f32 v[54:55], v[40:41], v[50:51], v[58:59] neg_lo:[0,0,1] neg_hi:[0,0,1]
	v_pk_mul_f32 v[42:43], v[42:43], v[210:211]
	v_pk_mul_f32 v[40:41], v[40:41], v[208:209]
	v_pk_fma_f32 v[34:35], v[34:35], v[52:53], v[42:43]
	v_pk_fma_f32 v[32:33], v[32:33], v[50:51], v[40:41]
	v_mov_b64_e32 v[40:41], v[54:55]
	v_mov_b64_e32 v[44:45], v[62:63]
	v_mov_b64_e32 v[42:43], v[56:57]
	v_mov_b64_e32 v[46:47], v[64:65]
.LBB0_554:
	s_or_b64 exec, exec, s[30:31]
	global_store_dwordx4 v[214:215], v[216:219], off
	global_store_dwordx4 v[214:215], v[220:223], off offset:64
	v_mov_b32_e32 v50, v112
	v_mov_b32_e32 v51, v112
	v_mad_i64_i32 v[48:49], s[0:1], s61, v48, 0
	v_pk_mul_f32 v[46:47], v[50:51], v[46:47]
	v_pk_mul_f32 v[44:45], v[112:113], v[44:45]
	v_pk_mul_f32 v[52:53], v[50:51], v[42:43]
	v_pk_mul_f32 v[42:43], v[112:113], v[40:41]
	v_lshl_add_u64 v[224:225], v[48:49], 1, v[114:115]
	v_cvt_pk_bf16_f32 v226, v44, v45
	v_cvt_pk_bf16_f32 v227, v46, v47
	v_cvt_pk_bf16_f32 v228, v42, v43
	v_cvt_pk_bf16_f32 v229, v52, v53
	v_pk_mul_f32 v[38:39], v[50:51], v[38:39]
	v_pk_mul_f32 v[36:37], v[112:113], v[36:37]
	v_pk_mul_f32 v[40:41], v[50:51], v[34:35]
	v_pk_mul_f32 v[34:35], v[112:113], v[32:33]
	v_cvt_pk_bf16_f32 v230, v36, v37
	v_cvt_pk_bf16_f32 v231, v38, v39
	v_cvt_pk_bf16_f32 v232, v34, v35
	v_cvt_pk_bf16_f32 v233, v40, v41
	s_and_b64 vcc, exec, s[42:43]
	s_mov_b64 s[0:1], -1
	v_add_u32_e32 v32, 0xa0, v158
	s_cbranch_vccz .LBB0_559
	s_andn2_b64 vcc, exec, s[0:1]
	s_cbranch_vccz .LBB0_560

; DI unsigned pk2(float lo, float hi) { typedef float f2 __attribute__((ext_vector_type(2))); typedef __bf16 b2 __attribute__((ext_vector_type(2))); f2 v = {lo, hi}; b2 b = __builtin_convertvector(v, b2); return __builtin_bit_cast(unsigned, b); }
;     DI void operator()(const f32x4 (&acc)[2][2][4][2], const Unit& u, int wr, int wc, int fr, int fq) const {
;     ...
;                     if (fq == 0) { const float* t = trigD + (size_t)pos * 16;
; #pragma unroll
;                         for (int n = 0; n < 2; ++n) { const f32x4 c4 = *(const f32x4*)(t + 4 * n), s4 = *(const f32x4*)(t + 8 + 4 * n); const f32x4 x1 = v[0][n], x2 = v[1][n];
;                             v[0][n] = x1 * c4 - x2 * s4; v[1][n] = x1 * s4 + x2 * c4; } }
;                 } else if (isrot) { const float* t = trigR + (size_t)pos * 64 + 8 * fq;
; #pragma unroll
;                     for (int n = 0; n < 2; ++n) { const f32x4 c4 = *(const f32x4*)(t + 4 * n), s4 = *(const f32x4*)(t + 32 + 4 * n); const f32x4 x1 = v[0][n], x2 = v[1][n];
;                         v[0][n] = x1 * c4 - x2 * s4; v[1][n] = x1 * s4 + x2 * c4; }
;                 }
;                 bf16_t* rowp = base + (size_t)row * ld + col0;
; #pragma unroll
;                 for (int bj = 0; bj < 2; ++bj) { const f32x4 v0 = v[bj][0] * osc, v1 = v[bj][1] * osc;
;                     u32x4 o; o.x = pk2(v0[0], v0[1]); o.y = pk2(v0[2], v0[3]); o.z = pk2(v1[0], v1[1]); o.w = pk2(v1[2], v1[3]);
;                     *(u32x4*)(rowp + 32 * bj) = o; }
.LBB0_568:
	v_and_b32_e32 v192, s4, v32
	v_lshlrev_b64 v[36:37], s56, v[192:193]
	v_lshl_add_u64 v[50:51], v[34:35], 0, v[36:37]
	v_lshl_add_u64 v[42:43], v[50:51], 0, s[50:51]
	v_lshl_add_u64 v[212:213], v[50:51], 0, s[86:87]
	global_load_dwordx4 v[34:37], v[50:51], off offset:16
	global_load_dwordx4 v[38:41], v[50:51], off
	s_nop 0
	global_load_dwordx4 v[42:45], v[42:43], off
	global_load_dwordx4 v[208:211], v[212:213], off
	s_waitcnt vmcnt(0)
	v_pk_mul_f32 v[46:47], v[22:23], v[44:45]
	v_pk_mul_f32 v[52:53], v[20:21], v[42:43]
	v_pk_fma_f32 v[48:49], v[30:31], v[40:41], v[46:47] neg_lo:[0,0,1] neg_hi:[0,0,1]
	v_pk_fma_f32 v[46:47], v[28:29], v[38:39], v[52:53] neg_lo:[0,0,1] neg_hi:[0,0,1]
	v_pk_mul_f32 v[28:29], v[28:29], v[42:43]
	v_pk_mul_f32 v[30:31], v[30:31], v[44:45]
	v_pk_fma_f32 v[20:21], v[20:21], v[38:39], v[28:29]
	v_pk_fma_f32 v[22:23], v[22:23], v[40:41], v[30:31]
	v_pk_mul_f32 v[38:39], v[18:19], v[210:211]
	v_pk_mul_f32 v[42:43], v[16:17], v[208:209]
	v_pk_fma_f32 v[40:41], v[26:27], v[36:37], v[38:39] neg_lo:[0,0,1] neg_hi:[0,0,1]
	v_pk_fma_f32 v[38:39], v[24:25], v[34:35], v[42:43] neg_lo:[0,0,1] neg_hi:[0,0,1]
	v_pk_mul_f32 v[26:27], v[26:27], v[210:211]
	v_pk_mul_f32 v[24:25], v[24:25], v[208:209]
	v_pk_fma_f32 v[18:19], v[18:19], v[36:37], v[26:27]
	v_pk_fma_f32 v[16:17], v[16:17], v[34:35], v[24:25]
	v_mov_b64_e32 v[24:25], v[38:39]
	v_mov_b64_e32 v[28:29], v[46:47]
	v_mov_b64_e32 v[26:27], v[40:41]
	v_mov_b64_e32 v[30:31], v[48:49]
.LBB0_569:
	s_or_b64 exec, exec, s[30:31]
	global_store_dwordx4 v[224:225], v[226:229], off
	global_store_dwordx4 v[224:225], v[230:233], off offset:64
	v_mov_b32_e32 v34, v112
	v_mov_b32_e32 v35, v112
	v_mad_i64_i32 v[32:33], s[0:1], s61, v32, 0
	v_pk_mul_f32 v[30:31], v[34:35], v[30:31]
	v_pk_mul_f32 v[28:29], v[112:113], v[28:29]
	v_pk_mul_f32 v[36:37], v[34:35], v[26:27]
	v_pk_mul_f32 v[26:27], v[112:113], v[24:25]
	v_lshl_add_u64 v[214:215], v[32:33], 1, v[114:115]
	v_cvt_pk_bf16_f32 v216, v28, v29
	v_cvt_pk_bf16_f32 v217, v30, v31
	v_cvt_pk_bf16_f32 v218, v26, v27
	v_cvt_pk_bf16_f32 v219, v36, v37
	v_pk_mul_f32 v[22:23], v[34:35], v[22:23]
	v_pk_mul_f32 v[20:21], v[112:113], v[20:21]
	v_pk_mul_f32 v[24:25], v[34:35], v[18:19]
	v_pk_mul_f32 v[18:19], v[112:113], v[16:17]
	v_cvt_pk_bf16_f32 v220, v20, v21
	v_cvt_pk_bf16_f32 v221, v22, v23
	v_cvt_pk_bf16_f32 v222, v18, v19
	v_cvt_pk_bf16_f32 v223, v24, v25
	s_and_b64 vcc, exec, s[42:43]
	s_mov_b64 s[0:1], -1
	v_add_u32_e32 v16, 0xb0, v158
	s_cbranch_vccz .LBB0_574
	s_andn2_b64 vcc, exec, s[0:1]
	s_cbranch_vccz .LBB0_575

; DI unsigned pk2(float lo, float hi) { typedef float f2 __attribute__((ext_vector_type(2))); typedef __bf16 b2 __attribute__((ext_vector_type(2))); f2 v = {lo, hi}; b2 b = __builtin_convertvector(v, b2); return __builtin_bit_cast(unsigned, b); }
;     DI void operator()(const f32x4 (&acc)[2][2][4][2], const Unit& u, int wr, int wc, int fr, int fq) const {
;     ...
;                     if (fq == 0) { const float* t = trigD + (size_t)pos * 16;
; #pragma unroll
;                         for (int n = 0; n < 2; ++n) { const f32x4 c4 = *(const f32x4*)(t + 4 * n), s4 = *(const f32x4*)(t + 8 + 4 * n); const f32x4 x1 = v[0][n], x2 = v[1][n];
;                             v[0][n] = x1 * c4 - x2 * s4; v[1][n] = x1 * s4 + x2 * c4; } }
;                 } else if (isrot) { const float* t = trigR + (size_t)pos * 64 + 8 * fq;
; #pragma unroll
;                     for (int n = 0; n < 2; ++n) { const f32x4 c4 = *(const f32x4*)(t + 4 * n), s4 = *(const f32x4*)(t + 32 + 4 * n); const f32x4 x1 = v[0][n], x2 = v[1][n];
;                         v[0][n] = x1 * c4 - x2 * s4; v[1][n] = x1 * s4 + x2 * c4; }
;                 }
;                 bf16_t* rowp = base + (size_t)row * ld + col0;
; #pragma unroll
;                 for (int bj = 0; bj < 2; ++bj) { const f32x4 v0 = v[bj][0] * osc, v1 = v[bj][1] * osc;
;                     u32x4 o; o.x = pk2(v0[0], v0[1]); o.y = pk2(v0[2], v0[3]); o.z = pk2(v1[0], v1[1]); o.w = pk2(v1[2], v1[3]);
;                     *(u32x4*)(rowp + 32 * bj) = o; }
.LBB0_583:
	v_and_b32_e32 v192, s4, v16
	v_lshlrev_b64 v[20:21], s50, v[192:193]
	v_lshl_add_u64 v[34:35], v[18:19], 0, v[20:21]
	v_lshl_add_u64 v[26:27], v[34:35], 0, s[44:45]
	v_lshl_add_u64 v[212:213], v[34:35], 0, s[42:43]
	global_load_dwordx4 v[18:21], v[34:35], off offset:16
	global_load_dwordx4 v[22:25], v[34:35], off
	s_nop 0
	global_load_dwordx4 v[26:29], v[26:27], off
	global_load_dwordx4 v[208:211], v[212:213], off
	s_waitcnt vmcnt(0)
	v_pk_mul_f32 v[30:31], v[6:7], v[28:29]
	v_pk_mul_f32 v[36:37], v[4:5], v[26:27]
	v_pk_fma_f32 v[32:33], v[14:15], v[24:25], v[30:31] neg_lo:[0,0,1] neg_hi:[0,0,1]
	v_pk_fma_f32 v[30:31], v[12:13], v[22:23], v[36:37] neg_lo:[0,0,1] neg_hi:[0,0,1]
	v_pk_mul_f32 v[12:13], v[12:13], v[26:27]
	v_pk_mul_f32 v[14:15], v[14:15], v[28:29]
	v_pk_fma_f32 v[4:5], v[4:5], v[22:23], v[12:13]
	v_pk_fma_f32 v[6:7], v[6:7], v[24:25], v[14:15]
	v_pk_mul_f32 v[22:23], v[2:3], v[210:211]
	v_pk_mul_f32 v[26:27], v[0:1], v[208:209]
	v_pk_fma_f32 v[24:25], v[10:11], v[20:21], v[22:23] neg_lo:[0,0,1] neg_hi:[0,0,1]
	v_pk_fma_f32 v[22:23], v[8:9], v[18:19], v[26:27] neg_lo:[0,0,1] neg_hi:[0,0,1]
	v_pk_mul_f32 v[10:11], v[10:11], v[210:211]
	v_pk_mul_f32 v[8:9], v[8:9], v[208:209]
	v_pk_fma_f32 v[2:3], v[2:3], v[20:21], v[10:11]
	v_pk_fma_f32 v[0:1], v[0:1], v[18:19], v[8:9]
	v_mov_b64_e32 v[8:9], v[22:23]
	v_mov_b64_e32 v[12:13], v[30:31]
	v_mov_b64_e32 v[10:11], v[24:25]
	v_mov_b64_e32 v[14:15], v[32:33]
.LBB0_584:
	s_or_b64 exec, exec, s[30:31]
	global_store_dwordx4 v[214:215], v[216:219], off
	global_store_dwordx4 v[214:215], v[220:223], off offset:64
	v_mov_b32_e32 v18, v112
	v_mov_b32_e32 v19, v112
	v_mad_i64_i32 v[16:17], s[0:1], s61, v16, 0
	v_pk_mul_f32 v[14:15], v[18:19], v[14:15]
	v_pk_mul_f32 v[12:13], v[112:113], v[12:13]
	v_pk_mul_f32 v[20:21], v[18:19], v[10:11]
	v_pk_mul_f32 v[10:11], v[112:113], v[8:9]
	v_lshl_add_u64 v[16:17], v[16:17], 1, v[114:115]
	v_cvt_pk_bf16_f32 v8, v12, v13
	v_cvt_pk_bf16_f32 v9, v14, v15
	v_cvt_pk_bf16_f32 v10, v10, v11
	v_cvt_pk_bf16_f32 v11, v20, v21
	global_store_dwordx4 v[16:17], v[8:11], off
	v_pk_mul_f32 v[6:7], v[18:19], v[6:7]
	v_pk_mul_f32 v[4:5], v[112:113], v[4:5]
	v_pk_mul_f32 v[8:9], v[18:19], v[2:3]
	v_pk_mul_f32 v[2:3], v[112:113], v[0:1]
	v_cvt_pk_bf16_f32 v0, v4, v5
	v_cvt_pk_bf16_f32 v1, v6, v7
	v_cvt_pk_bf16_f32 v2, v2, v3
	v_cvt_pk_bf16_f32 v3, v8, v9
	s_andn2_b64 vcc, exec, s[40:41]
	s_mov_b64 s[0:1], -1
	global_store_dwordx4 v[16:17], v[0:3], off offset:64
	s_cbranch_vccnz .LBB0_455
	v_readlane_b32 s0, v255, 28
	v_readlane_b32 s1, v255, 29
	s_andn2_b64 vcc, exec, s[0:1]
	s_cbranch_vccnz .LBB0_454
	s_barrier
	s_branch .LBB0_454
